# P2 phase-transition trims: skip statically-empty queue phases (q0 for non-streamers, q2 for streamers), unwaited norm-max load at P2 start
# speedup vs baseline: 1.0014x; 1.0014x over previous
; #define LDS_AS __attribute__((address_space(3)))
; __global__ void __launch_bounds__(512, 2) hymba_mega(Params p) {
;     ...
;     for (int rep = 0; rep < 1 + DUP_P2; ++rep) {
;         const int cq = rep * 64;
;         LDS_AS int* sunit = (LDS_AS int*)((LDS_AS char*)smem + SM_UNIT_OFF);
;     ...
;         const bool streamer = ((blockIdx.x >> 3) & 3) == 0;
;         for (int ph = 0; ph < 4; ++ph) {
;             const int qi = streamer ? (ph == 0 ? 0 : ph == 1 ? 2 : ph == 2 ? 1 : 3) : (ph == 0 ? 1 : ph == 1 ? 0 : ph == 2 ? 2 : 3);
.LBB0_400:
	s_or_b64 exec, exec, s[0:1]
	v_mov_b32_e32 v251, 0x180
	global_load_dwordx2 v[254:255], v251, s[56:57] sc0 sc1
	s_and_b32 s0, s2, 24
	s_cmp_lg_u32 s0, 0
	s_mov_b32 s0, 0x20040
	s_cselect_b64 s[12:13], -1, 0
	v_bfe_u32 v141, v0, 20, 10
	v_bfe_u32 v143, v0, 10, 10
	s_add_i32 s63, s0, 0x100
	s_mov_b32 s0, 0x20044
	v_mbcnt_lo_u32_b32 v0, -1, 0
	s_mov_b32 s11, 0
	v_mov_b32_e32 v131, 0
	s_movk_i32 s62, 0x100
	s_movk_i32 s66, 0x21f
	s_movk_i32 s67, 0x1000
	s_movk_i32 s88, 0x1010
	s_mov_b64 s[14:15], 0x10000
	s_mov_b64 s[16:17], 0x20000
	s_mov_b64 s[20:21], 0x30000
	s_movk_i32 s89, 0x90
	s_mov_b32 s90, 0xc2400000
	s_movk_i32 s91, 0x1200
	s_mov_b64 s[22:23], 0x1000
	s_mov_b32 s92, 0x12000
	s_mov_b32 s93, 0xf149f2ca
	s_movk_i32 s94, 0x2100
	s_add_i32 s95, s0, 0x100
	s_mov_b32 s96, 0x10000
	s_mov_b64 s[24:25], 0x10900
	s_mov_b64 s[26:27], 0x10940
	s_mov_b64 s[28:29], 0x1c00
	v_mov_b32_e32 v145, 0xff800000
	v_mbcnt_hi_u32_b32 v174, -1, v0
	v_mov_b32_e32 v147, 0x100
	v_mov_b32_e32 v175, 0x42000
	s_mov_b32 s97, 0
	s_and_b64 vcc, exec, s[12:13]
	s_cbranch_vccnz .Lstr_s97
	s_mov_b32 s97, -1

; __global__ void __launch_bounds__(512, 2) hymba_mega(Params p) {
;     ...
;         const bool streamer = ((blockIdx.x >> 3) & 3) == 0;
;         for (int ph = 0; ph < 4; ++ph) {
;             const int qi = streamer ? (ph == 0 ? 0 : ph == 1 ? 2 : ph == 2 ? 1 : 3) : (ph == 0 ? 1 : ph == 1 ? 0 : ph == 2 ? 2 : 3);
.LBB0_402:
	s_mov_b32 s99, 0x7fffffff
	s_cmp_eq_u32 s97, -1
	s_cselect_b32 s99, 1, s99
	s_and_b64 vcc, exec, s[12:13]
	s_mov_b64 s[0:1], -1
	s_cbranch_vccz .LBB0_409
	s_cmp_eq_u32 s97, 0
	s_cselect_b32 s38, 2, 3
	s_cmp_eq_u32 s97, 1
	s_cselect_b32 s38, 1, s38
	s_cmp_eq_u32 s97, 2
	s_cselect_b32 s38, 4, s38

; #define QUEUE_LOOP(QI, NUNITS, BODY) \
;         for (;;) { \
;             __syncthreads(); \
;             if (tid == 0) *sunit = (int)atomicAdd(p.ctrl + cq + (QI), 1u); \
;             __syncthreads(); \
;             const int u = *sunit; \
;             if (u >= (NUNITS)) break; \
;             BODY; \
;         }
; __global__ void __launch_bounds__(512, 2) hymba_mega(Params p) {
;     ...
;         for (int ph = 0; ph < 4; ++ph) {
;             const int qi = streamer ? (ph == 0 ? 0 : ph == 1 ? 2 : ph == 2 ? 1 : 3) : (ph == 0 ? 1 : ph == 1 ? 0 : ph == 2 ? 2 : 3);
;             if (qi == 0) { QUEUE_LOOP(0, NU_SF, sample_unit<1>(p, u / NSPLIT, u % NSPLIT, smem, cq)) }
;             else if (qi == 1) { QUEUE_LOOP(1, NU_PF, prompt_unit<1>(p, (u & 31) >> 3, u & 7, 16 - (u >> 5), smem)) }
;             else if (qi == 2) { QUEUE_LOOP(2, NU_SS, sample_unit<0>(p, u, 0, smem)) }
;             else { QUEUE_LOOP(3, NU_PS, prompt_sb_unit(p, (u & 31) >> 3, u & 7, 16 - (u >> 5), smem)) }
.LBB0_409:
	s_and_b64 vcc, exec, s[0:1]
	s_cbranch_vccz .LBB0_415
	s_cmp_eq_u32 s97, 0
	s_cselect_b32 s38, 0, 3
	s_cmp_eq_u32 s97, 1
	s_cselect_b32 s38, 4, s38
	s_cmp_eq_u32 s97, 2
	s_cselect_b32 s38, 1, s38
.LBB0_415:
	s_cmp_eq_u32 s38, 4
	s_cbranch_scc1 .LBB0_401
	s_cmp_lt_i32 s38, 2
	s_mov_b64 s[0:1], -1
	s_cbranch_scc1 .LBB0_436
	s_cmp_gt_i32 s38, 2
	s_cbranch_scc1 .LBB0_420
	s_and_b64 vcc, exec, s[0:1]
	s_cbranch_vccnz .LBB0_482
	s_branch .LBB0_435

; #define LDS_AS __attribute__((address_space(3)))
; template <int MODE>
; DI void prompt_unit(const Params& p, int b, int h, int qt, char* smem) {
;     ...
;     const int kt_max = (4 * qt + 3) < 64 ? (4 * qt + 3) : 64;
;     const float* cb = p.c2p + (size_t)(b * 8 + h) * LPAD;
;     float cref = 0.f;
;     if (MODE == 1) cref = cb[t0 < LP ? t0 : LP - 1];
;     u32x4 rk, rv; float rbias = 0.f;
;     const int r0 = tid >> 3, c0 = tid & 7;
;     auto pload = [&](int kt) {
;         const bf16_t* kb = p.u + (rowb + (size_t)kt * 64 + r0) * NU + c0 * 8;
;         rk = *(const u32x4*)(kb + kcol); rv = *(const u32x4*)(kb + vcol);
;         if (MODE == 1 && tid < 64) rbias = cref - cb[kt * 64 + tid];
;     };
;     auto pstore = [&](int sg) {
;         LDS_AS char* base = lb + sg * PSTG + r0 * 144 + c0 * 16;
;         *(LDS_AS u32x4*)(base) = rk; *(LDS_AS u32x4*)(base + 9216) = rv;
;         if (MODE == 1 && tid < 64) *(LDS_AS float*)(lb + sg * PSTG + 18432 + tid * 4) = rbias;
;     };
;     __syncthreads();
;     pload(kt_max); pstore(0);
;     __syncthreads();
;     int stg = 0;
;     bool wdone = !wave_valid;
;     ...
;         if (kt > 0) pload(kt - 1);
;         if (!wdone) {
;             LDS_AS const char* sb = lb + stg * PSTG;
;             if (MODE == 1 && kt * 64 + 63 < wq0) attn_tile64_fox(sb, sb + 9216, sb + 18432, q, st, lane);
.Lfoxp_entry:
	s_cmp_eq_u32 s100, -2
	s_cbranch_scc1 .LBB0_548
	s_mul_i32 s38, s98, 0x4900
	s_addk_i32 s38, 0x100
	s_mov_b32 s39, 0x9300
	s_xor_b32 s46, s98, 1
	s_mul_i32 s46, s46, 0x4900
	s_addk_i32 s46, 0x100
	s_add_i32 s10, s100, 1
	s_mov_b32 s42, 0
	s_cmp_lt_u32 s100, 22
	s_cbranch_scc1 .Lfsk_none
	v_cmp_gt_i32_e32 vcc, s88, v88
	v_mov_b32_e32 v164, 0x7f800000
	s_nop 0
	v_cndmask_b32_e32 v164, v164, v94, vcc
	v_xor_b32_e32 v165, 1, v174
	v_lshlrev_b32_e32 v165, 2, v165
	ds_bpermute_b32 v244, v165, v164
	s_waitcnt lgkmcnt(0)
	v_min_f32_e32 v164, v164, v244
	v_xor_b32_e32 v165, 2, v174
	v_lshlrev_b32_e32 v165, 2, v165
	ds_bpermute_b32 v244, v165, v164
	s_waitcnt lgkmcnt(0)
	v_min_f32_e32 v164, v164, v244
	v_xor_b32_e32 v165, 4, v174
	v_lshlrev_b32_e32 v165, 2, v165
	ds_bpermute_b32 v244, v165, v164
	s_waitcnt lgkmcnt(0)
	v_min_f32_e32 v164, v164, v244
	v_xor_b32_e32 v165, 8, v174
	v_lshlrev_b32_e32 v165, 2, v165
	ds_bpermute_b32 v244, v165, v164
	s_waitcnt lgkmcnt(0)
	v_min_f32_e32 v164, v164, v244
	v_xor_b32_e32 v165, 16, v174
	v_lshlrev_b32_e32 v165, 2, v165
	ds_bpermute_b32 v244, v165, v164
	s_waitcnt lgkmcnt(0)
	v_min_f32_e32 v164, v164, v244
	v_lshrrev_b32_e32 v165, 6, v138
	v_lshlrev_b32_e32 v165, 2, v165
	v_add_u32_e32 v165, 0x1f000, v165
	ds_write_b32 v165, v164
	s_waitcnt lgkmcnt(0)
	s_barrier
	v_mov_b32_e32 v165, 0x1f000
	ds_read_b128 v[132:135], v165
	ds_read_b128 v[160:163], v165 offset:16
	v_mul_f32_e32 v136, v254, v255
	v_sqrt_f32_e32 v136, v136
	s_waitcnt lgkmcnt(0)
	v_min3_f32 v164, v132, v133, v134
	v_min3_f32 v164, v164, v135, v160
	v_min3_f32 v164, v164, v161, v162
	v_min_f32_e32 v164, v164, v163
	v_mul_f32_e32 v136, 0x3ebc5bb7, v136
	v_add_f32_e32 v136, v136, v95
	v_add_f32_e32 v136, 0x43190000, v136
	v_sub_f32_e32 v136, v136, v164
	v_cmp_gt_f32_e32 vcc, v251, v136
	s_not_b64 s[42:43], vcc
	s_ff1_i32_b64 s42, s[42:43]
	s_cmp_lt_i32 s42, 0
	s_cselect_b32 s42, 64, s42
	s_min_i32 s42, s42, s100
	s_and_b32 s42, s42, -2
